# proj last-column tiles (pn=48) run a K-loop copy without the all-zero-padding MFMAs; coop_attn staging stores wait only for the older load set
# speedup vs baseline: 1.0080x; 1.0080x over previous
.LBB0_211:
	s_cmp_lg_u64 s[58:59], 0
	s_cbranch_scc0 .Lrw_slc1_orig
	s_waitcnt vmcnt(7)
	ds_write_b128 v216, v[144:147] offset:35840
	s_waitcnt vmcnt(6)
	ds_write_b128 v216, v[148:151] offset:44544
	s_waitcnt vmcnt(5)
	ds_write_b128 v246, v[152:155] offset:53248
	s_waitcnt vmcnt(4)
	ds_write_b128 v246, v[156:159] offset:62464
	s_branch .Lrw_slc1_done

.Lrw_slc1_done:
.LBB0_212:
	s_cmp_lt_i32 s11, 0
	s_waitcnt lgkmcnt(0)
	s_barrier
	s_cbranch_scc1 .LBB0_200
	s_add_u32 s2, s52, -1
	s_addc_u32 s3, s53, -1
	s_and_b64 s[52:53], s[2:3], s[52:53]
	s_ff1_i32_b64 s2, s[52:53]
	s_cmp_lg_u64 s[52:53], 0
	s_cselect_b32 s34, s2, -1
	s_cmp_lt_i32 s34, 0
	s_cbranch_scc1 .LBB0_215
	v_lshl_add_u32 v14, s34, 6, v185
	v_ashrrev_i32_e32 v15, 31, v14
	v_lshlrev_b64 v[14:15], 8, v[14:15]
	v_lshl_or_b32 v14, v168, 1, v14
	v_lshl_add_u64 v[80:81], s[22:23], 0, v[14:15]
	v_add_co_u32_e32 v82, vcc, 0x2000, v80
	v_lshl_add_u64 v[14:15], s[24:25], 0, v[14:15]
	s_nop 0
	v_addc_co_u32_e32 v83, vcc, 0, v81, vcc
	global_load_dwordx4 v[144:147], v[80:81], off
	global_load_dwordx4 v[148:151], v[82:83], off
	v_add_co_u32_e32 v80, vcc, 0x2000, v14
	s_nop 1
	v_addc_co_u32_e32 v81, vcc, 0, v15, vcc
	global_load_dwordx4 v[152:155], v[14:15], off
	global_load_dwordx4 v[156:159], v[80:81], off

.LBB0_223:
	s_cmp_gt_i32 s34, -1
	s_cbranch_scc0 .Lrw_slc2_orig
	s_waitcnt vmcnt(7)
	ds_write_b128 v216, v[2:5]
	s_waitcnt vmcnt(6)
	ds_write_b128 v216, v[6:9] offset:8704
	s_waitcnt vmcnt(5)
	ds_write_b128 v246, v[10:13] offset:17408
	s_waitcnt vmcnt(4)
	ds_write_b128 v246, v[160:163] offset:26624
	s_branch .Lrw_slc2_done

.Lrw_slc2_done:
.LBB0_224:
	s_add_u32 s2, s52, -1
	s_addc_u32 s3, s53, -1
	s_and_b64 s[52:53], s[2:3], s[52:53]
	s_waitcnt lgkmcnt(0)
	s_barrier
	s_and_b64 vcc, exec, s[30:31]
	s_mov_b32 s14, s10
	s_mov_b32 s11, s34
	s_cbranch_vccz .LBB0_201
	s_branch .LBB0_228

; #define MFMA32(a, b, c) __builtin_amdgcn_mfma_f32_32x32x16_bf16((a), (b), (c), 0, 0, 0)
; template <int C>
; DI void pv_block2(f32x16& oa, f32x16& ob, unsigned vbase, const bf16x8& pf0, const bf16x8& pf1) {
;   s16x4 r[8];
;   tr_read8<64 * C>(vbase, r);
;   const bf16x8 a0 = __builtin_shufflevector(r[0], r[1], 0, 1, 2, 3, 4, 5, 6, 7);
;   const bf16x8 a1 = __builtin_shufflevector(r[2], r[3], 0, 1, 2, 3, 4, 5, 6, 7);
;   const bf16x8 b0 = __builtin_shufflevector(r[4], r[5], 0, 1, 2, 3, 4, 5, 6, 7);
;   const bf16x8 b1 = __builtin_shufflevector(r[6], r[7], 0, 1, 2, 3, 4, 5, 6, 7);
;   oa = MFMA32(a0, pf0, oa);
;   ob = MFMA32(b0, pf0, ob);
;   oa = MFMA32(a1, pf1, oa);
;   ob = MFMA32(b1, pf1, ob);
; }
; DI void coop_compute(AttnAcc& a, const bf16x8 (&qf)[8], char* stg, const int lo, const int hi, int lane) {
;     ...
;   const float alpha = __builtin_amdgcn_exp2f(a.m - msafe);
;   a.m = mx;
;   float ls = 0.f;
; #pragma unroll
;   for (int hf = 0; hf < 2; ++hf)
; #pragma unroll
;     for (int i = 0; i < 16; ++i) { const float pv = __builtin_amdgcn_exp2f(st[hf][i] - msafe); st[hf][i] = pv; ls += pv; }
;   a.l = a.l * alpha + ls;
;   if (!__all(alpha == 1.f)) {
; #pragma unroll
;     for (int c = 0; c < 4; ++c) a.o[c] *= alpha;
;   }
;   pv_tile(a, st[0], stg + STG_K, lane);
;   pv_tile(a, st[1], stg + STG_K + 32 * VSTRIDE, lane);
.LBB0_252:
	v_sub_f32_e32 v67, v190, v175
	v_sub_f32_e32 v68, v191, v175
	v_sub_f32_e32 v69, v192, v175
	v_sub_f32_e32 v70, v193, v175
	v_sub_f32_e32 v71, v194, v175
	v_sub_f32_e32 v72, v195, v175
	v_sub_f32_e32 v73, v196, v175
	v_sub_f32_e32 v74, v197, v175
	v_exp_f32_e32 v67, v67
	v_exp_f32_e32 v68, v68
	v_exp_f32_e32 v69, v69
	v_exp_f32_e32 v70, v70
	v_exp_f32_e32 v71, v71
	v_exp_f32_e32 v72, v72
	v_exp_f32_e32 v73, v73
	v_exp_f32_e32 v74, v74
	v_cvt_pk_bf16_f32 v190, v67, v68
	v_cvt_pk_bf16_f32 v191, v69, v70
	v_cvt_pk_bf16_f32 v192, v71, v72
	v_cvt_pk_bf16_f32 v193, v73, v74
	s_waitcnt lgkmcnt(0)
	v_sub_f32_e32 v75, v198, v175
	v_sub_f32_e32 v76, v199, v175
	v_sub_f32_e32 v77, v200, v175
	v_sub_f32_e32 v78, v201, v175
	v_sub_f32_e32 v79, v202, v175
	v_sub_f32_e32 v80, v203, v175
	v_sub_f32_e32 v81, v204, v175
	v_sub_f32_e32 v82, v205, v175
	v_sub_f32_e32 v83, v206, v175
	v_sub_f32_e32 v84, v207, v175
	v_sub_f32_e32 v85, v208, v175
	v_sub_f32_e32 v86, v209, v175
	v_sub_f32_e32 v87, v210, v175
	v_sub_f32_e32 v88, v211, v175
	v_sub_f32_e32 v89, v212, v175
	v_sub_f32_e32 v90, v213, v175
	ds_read_b64_tr_b16 v[210:211], v242 offset:0
	ds_read_b64_tr_b16 v[212:213], v242 offset:0x900
	ds_read_b64_tr_b16 v[206:207], v242 offset:0x1200
	ds_read_b64_tr_b16 v[208:209], v242 offset:0x1b00
	ds_read_b64_tr_b16 v[202:203], v242 offset:64
	ds_read_b64_tr_b16 v[204:205], v242 offset:0x940
	ds_read_b64_tr_b16 v[198:199], v242 offset:0x1240
	ds_read_b64_tr_b16 v[200:201], v242 offset:0x1b40
	s_waitcnt lgkmcnt(0)
	v_exp_f32_e32 v75, v75
	v_mfma_f32_32x32x16_bf16 v[50:65], v[210:213], v[190:193], v[50:65]
	v_exp_f32_e32 v76, v76
	v_exp_f32_e32 v77, v77
	v_exp_f32_e32 v78, v78
	v_exp_f32_e32 v79, v79
	v_exp_f32_e32 v80, v80
	v_exp_f32_e32 v81, v81
	v_exp_f32_e32 v82, v82
	v_mfma_f32_32x32x16_bf16 v[34:49], v[202:205], v[190:193], v[34:49]
	v_cvt_pk_bf16_f32 v194, v75, v76
	v_cvt_pk_bf16_f32 v195, v77, v78
	v_cvt_pk_bf16_f32 v196, v79, v80
	v_cvt_pk_bf16_f32 v197, v81, v82
	v_exp_f32_e32 v83, v83
	v_exp_f32_e32 v84, v84
	v_exp_f32_e32 v85, v85
	v_mfma_f32_32x32x16_bf16 v[50:65], v[206:209], v[194:197], v[50:65]
	v_exp_f32_e32 v86, v86
	v_exp_f32_e32 v87, v87
	v_exp_f32_e32 v88, v88
	v_exp_f32_e32 v89, v89
	v_exp_f32_e32 v90, v90
	v_sub_f32_e32 v91, v214, v175
	v_sub_f32_e32 v92, v215, v175
	v_mfma_f32_32x32x16_bf16 v[34:49], v[198:201], v[194:197], v[34:49]
	ds_read_b64_tr_b16 v[210:211], v242 offset:0x80
	ds_read_b64_tr_b16 v[212:213], v242 offset:0x980
	ds_read_b64_tr_b16 v[206:207], v242 offset:0x1280
	ds_read_b64_tr_b16 v[208:209], v242 offset:0x1b80
	ds_read_b64_tr_b16 v[202:203], v242 offset:0xc0
	ds_read_b64_tr_b16 v[204:205], v242 offset:0x9c0
	ds_read_b64_tr_b16 v[198:199], v242 offset:0x12c0
	ds_read_b64_tr_b16 v[200:201], v242 offset:0x1bc0
	s_waitcnt lgkmcnt(0)
	s_waitcnt lgkmcnt(0)
	v_sub_f32_e32 v93, v216, v175
	v_sub_f32_e32 v94, v217, v175
	v_sub_f32_e32 v95, v218, v175
	v_sub_f32_e32 v96, v219, v175
	v_sub_f32_e32 v97, v220, v175
	v_mfma_f32_32x32x16_bf16 v[18:33], v[210:213], v[190:193], v[18:33]
	v_sub_f32_e32 v175, v221, v175
	v_exp_f32_e32 v91, v91
	v_exp_f32_e32 v92, v92
	v_exp_f32_e32 v93, v93
	v_exp_f32_e32 v94, v94
	v_exp_f32_e32 v95, v95
	v_exp_f32_e32 v96, v96
	v_mfma_f32_32x32x16_bf16 v[2:17], v[202:205], v[190:193], v[2:17]
	v_cvt_pk_bf16_f32 v190, v83, v84
	v_cvt_pk_bf16_f32 v191, v85, v86
	v_cvt_pk_bf16_f32 v192, v87, v88
	v_cvt_pk_bf16_f32 v193, v89, v90
	v_exp_f32_e32 v97, v97
	v_exp_f32_e32 v175, v175
	s_cmp_lt_i32 s20, 0
	v_mfma_f32_32x32x16_bf16 v[18:33], v[206:209], v[194:197], v[18:33]
	v_mfma_f32_32x32x16_bf16 v[2:17], v[198:201], v[194:197], v[2:17]
	ds_read_b64_tr_b16 v[210:211], v244 offset:0
	ds_read_b64_tr_b16 v[212:213], v244 offset:0x900
	ds_read_b64_tr_b16 v[206:207], v244 offset:0x1200
	ds_read_b64_tr_b16 v[208:209], v244 offset:0x1b00
	ds_read_b64_tr_b16 v[202:203], v244 offset:64
	ds_read_b64_tr_b16 v[204:205], v244 offset:0x940
	ds_read_b64_tr_b16 v[198:199], v244 offset:0x1240
	ds_read_b64_tr_b16 v[200:201], v244 offset:0x1b40
	s_waitcnt lgkmcnt(0)
	v_cvt_pk_bf16_f32 v194, v91, v92
	v_cvt_pk_bf16_f32 v195, v93, v94
	v_cvt_pk_bf16_f32 v196, v95, v96
	v_cvt_pk_bf16_f32 v197, v97, v175
	v_mfma_f32_32x32x16_bf16 v[50:65], v[210:213], v[190:193], v[50:65]
	v_mfma_f32_32x32x16_bf16 v[34:49], v[202:205], v[190:193], v[34:49]
	v_mfma_f32_32x32x16_bf16 v[50:65], v[206:209], v[194:197], v[50:65]
	v_mfma_f32_32x32x16_bf16 v[34:49], v[198:201], v[194:197], v[34:49]
	ds_read_b64_tr_b16 v[210:211], v244 offset:0x80
	ds_read_b64_tr_b16 v[212:213], v244 offset:0x980
	ds_read_b64_tr_b16 v[206:207], v244 offset:0x1280
	ds_read_b64_tr_b16 v[208:209], v244 offset:0x1b80
	ds_read_b64_tr_b16 v[202:203], v244 offset:0xc0
	ds_read_b64_tr_b16 v[204:205], v244 offset:0x9c0
	ds_read_b64_tr_b16 v[198:199], v244 offset:0x12c0
	ds_read_b64_tr_b16 v[200:201], v244 offset:0x1bc0
	s_waitcnt lgkmcnt(0)
	s_nop 0
	v_mfma_f32_32x32x16_bf16 v[18:33], v[210:213], v[190:193], v[18:33]
	v_mfma_f32_32x32x16_bf16 v[2:17], v[202:205], v[190:193], v[2:17]
	v_mfma_f32_32x32x16_bf16 v[18:33], v[206:209], v[194:197], v[18:33]
	v_mfma_f32_32x32x16_bf16 v[2:17], v[198:201], v[194:197], v[2:17]
	s_cbranch_scc1 .LBB0_254
	s_cmp_lg_u64 s[14:15], 0
	s_cbranch_scc0 .Lrw_win1_orig
	s_waitcnt vmcnt(7)
	ds_write_b128 v241, v[130:133] offset:35840
	s_waitcnt vmcnt(6)
	ds_write_b128 v241, v[134:137] offset:44544
	s_waitcnt vmcnt(5)
	ds_write_b128 v238, v[138:141] offset:53248
	s_waitcnt vmcnt(4)
	ds_write_b128 v238, v[142:145] offset:62464
	s_branch .Lrw_win1_done
; DI void coop_compute(AttnAcc& a, const bf16x8 (&qf)[8], char* stg, const int lo, const int hi, int lane) {
;     ...
;   for (int hf = 0; hf < 2; ++hf)
; #pragma unroll
;     for (int i = 0; i < 16; ++i) { const float pv = __builtin_amdgcn_exp2f(st[hf][i] - msafe); st[hf][i] = pv; ls += pv; }
;   a.l = a.l * alpha + ls;
.Lrw_win1_orig:
	s_waitcnt vmcnt(3)
	ds_write_b128 v241, v[130:133] offset:35840
	s_waitcnt vmcnt(2)
	ds_write_b128 v241, v[134:137] offset:44544
	s_waitcnt vmcnt(1)
	ds_write_b128 v238, v[138:141] offset:53248
	s_waitcnt vmcnt(0)
	ds_write_b128 v238, v[142:145] offset:62464
.Lrw_win1_done:
.LBB0_254:
	v_add_f32_e32 v67, 0, v67
	v_add_f32_e32 v67, v68, v67
	v_add_f32_e32 v67, v69, v67
	v_add_f32_e32 v67, v70, v67
	v_add_f32_e32 v67, v71, v67
	v_add_f32_e32 v67, v72, v67
	v_add_f32_e32 v67, v73, v67
	v_add_f32_e32 v67, v74, v67
	v_add_f32_e32 v67, v75, v67
	v_add_f32_e32 v67, v76, v67
	v_add_f32_e32 v67, v77, v67
	v_add_f32_e32 v67, v78, v67
	v_add_f32_e32 v67, v79, v67
	v_add_f32_e32 v67, v80, v67
	v_add_f32_e32 v67, v81, v67
	v_add_f32_e32 v67, v82, v67
	v_add_f32_e32 v67, v83, v67
	v_add_f32_e32 v67, v84, v67
	v_add_f32_e32 v67, v85, v67
	v_add_f32_e32 v67, v86, v67
	v_add_f32_e32 v67, v87, v67
	v_add_f32_e32 v67, v88, v67
	v_add_f32_e32 v67, v89, v67
	v_add_f32_e32 v67, v90, v67
	v_add_f32_e32 v67, v91, v67
	v_add_f32_e32 v67, v92, v67
	v_add_f32_e32 v67, v93, v67
	v_add_f32_e32 v67, v94, v67
	v_add_f32_e32 v67, v95, v67
	v_add_f32_e32 v67, v96, v67
	v_add_f32_e32 v67, v97, v67
	v_add_f32_e32 v175, v175, v67
	v_fmac_f32_e32 v175, v181, v66
	s_cmp_lt_i32 s20, 0
	s_mov_b64 s[0:1], -1
	s_waitcnt lgkmcnt(0)
	s_barrier
	s_cbranch_scc1 .LBB0_243
	s_add_u32 s0, s16, -1
	s_addc_u32 s1, s17, -1
	s_and_b64 s[16:17], s[0:1], s[16:17]
	s_ff1_i32_b64 s0, s[16:17]
	s_cmp_lg_u64 s[16:17], 0
	s_cselect_b32 s21, s0, -1
	s_cmp_lt_i32 s21, 0
	s_cbranch_scc1 .LBB0_257
	v_lshl_add_u32 v66, s21, 6, v165
	v_ashrrev_i32_e32 v67, 31, v66
	v_lshlrev_b64 v[66:67], 8, v[66:67]
	v_lshl_or_b32 v66, v162, 1, v66
	v_lshl_add_u64 v[68:69], s[8:9], 0, v[66:67]
	v_add_co_u32_e32 v70, vcc, 0x2000, v68
	v_lshl_add_u64 v[66:67], s[10:11], 0, v[66:67]
	s_nop 0
	v_addc_co_u32_e32 v71, vcc, 0, v69, vcc
	global_load_dwordx4 v[130:133], v[68:69], off
	global_load_dwordx4 v[134:137], v[70:71], off
	v_add_co_u32_e32 v68, vcc, 0x2000, v66
	s_nop 1
	v_addc_co_u32_e32 v69, vcc, 0, v67, vcc
	global_load_dwordx4 v[138:141], v[66:67], off
	global_load_dwordx4 v[142:145], v[68:69], off

; #define MFMA32(a, b, c) __builtin_amdgcn_mfma_f32_32x32x16_bf16((a), (b), (c), 0, 0, 0)
; template <int C>
; DI void pv_block2(f32x16& oa, f32x16& ob, unsigned vbase, const bf16x8& pf0, const bf16x8& pf1) {
;   s16x4 r[8];
;   tr_read8<64 * C>(vbase, r);
;   const bf16x8 a0 = __builtin_shufflevector(r[0], r[1], 0, 1, 2, 3, 4, 5, 6, 7);
;   const bf16x8 a1 = __builtin_shufflevector(r[2], r[3], 0, 1, 2, 3, 4, 5, 6, 7);
;   const bf16x8 b0 = __builtin_shufflevector(r[4], r[5], 0, 1, 2, 3, 4, 5, 6, 7);
;   const bf16x8 b1 = __builtin_shufflevector(r[6], r[7], 0, 1, 2, 3, 4, 5, 6, 7);
;   oa = MFMA32(a0, pf0, oa);
;   ob = MFMA32(b0, pf0, ob);
;   oa = MFMA32(a1, pf1, oa);
;   ob = MFMA32(b1, pf1, ob);
; }
; DI void coop_compute(AttnAcc& a, const bf16x8 (&qf)[8], char* stg, const int lo, const int hi, int lane) {
;     ...
;   const float alpha = __builtin_amdgcn_exp2f(a.m - msafe);
;   a.m = mx;
;   float ls = 0.f;
; #pragma unroll
;   for (int hf = 0; hf < 2; ++hf)
; #pragma unroll
;     for (int i = 0; i < 16; ++i) { const float pv = __builtin_amdgcn_exp2f(st[hf][i] - msafe); st[hf][i] = pv; ls += pv; }
;   a.l = a.l * alpha + ls;
;   if (!__all(alpha == 1.f)) {
; #pragma unroll
;     for (int c = 0; c < 4; ++c) a.o[c] *= alpha;
;   }
;   pv_tile(a, st[0], stg + STG_K, lane);
;   pv_tile(a, st[1], stg + STG_K + 32 * VSTRIDE, lane);
.LBB0_263:
	v_sub_f32_e32 v67, v190, v181
	v_sub_f32_e32 v68, v191, v181
	v_sub_f32_e32 v69, v192, v181
	v_sub_f32_e32 v70, v193, v181
	v_sub_f32_e32 v71, v194, v181
	v_sub_f32_e32 v72, v195, v181
	v_sub_f32_e32 v73, v196, v181
	v_sub_f32_e32 v74, v197, v181
	v_exp_f32_e32 v67, v67
	v_exp_f32_e32 v68, v68
	v_exp_f32_e32 v69, v69
	v_exp_f32_e32 v70, v70
	v_exp_f32_e32 v71, v71
	v_exp_f32_e32 v72, v72
	v_exp_f32_e32 v73, v73
	v_exp_f32_e32 v74, v74
	v_cvt_pk_bf16_f32 v190, v67, v68
	v_cvt_pk_bf16_f32 v191, v69, v70
	v_cvt_pk_bf16_f32 v192, v71, v72
	v_cvt_pk_bf16_f32 v193, v73, v74
	s_waitcnt lgkmcnt(0)
	v_sub_f32_e32 v75, v198, v181
	v_sub_f32_e32 v76, v199, v181
	v_sub_f32_e32 v77, v200, v181
	v_sub_f32_e32 v78, v201, v181
	v_sub_f32_e32 v79, v202, v181
	v_sub_f32_e32 v80, v203, v181
	v_sub_f32_e32 v81, v204, v181
	v_sub_f32_e32 v82, v205, v181
	v_sub_f32_e32 v83, v206, v181
	v_sub_f32_e32 v84, v207, v181
	v_sub_f32_e32 v85, v208, v181
	v_sub_f32_e32 v86, v209, v181
	v_sub_f32_e32 v87, v210, v181
	v_sub_f32_e32 v88, v211, v181
	v_sub_f32_e32 v89, v212, v181
	v_sub_f32_e32 v90, v213, v181
	ds_read_b64_tr_b16 v[210:211], v245 offset:0
	ds_read_b64_tr_b16 v[212:213], v245 offset:0x900
	ds_read_b64_tr_b16 v[206:207], v245 offset:0x1200
	ds_read_b64_tr_b16 v[208:209], v245 offset:0x1b00
	ds_read_b64_tr_b16 v[202:203], v245 offset:64
	ds_read_b64_tr_b16 v[204:205], v245 offset:0x940
	ds_read_b64_tr_b16 v[198:199], v245 offset:0x1240
	ds_read_b64_tr_b16 v[200:201], v245 offset:0x1b40
	s_waitcnt lgkmcnt(0)
	v_exp_f32_e32 v75, v75
	v_mfma_f32_32x32x16_bf16 v[50:65], v[210:213], v[190:193], v[50:65]
	v_exp_f32_e32 v76, v76
	v_exp_f32_e32 v77, v77
	v_exp_f32_e32 v78, v78
	v_exp_f32_e32 v79, v79
	v_exp_f32_e32 v80, v80
	v_exp_f32_e32 v81, v81
	v_exp_f32_e32 v82, v82
	v_mfma_f32_32x32x16_bf16 v[34:49], v[202:205], v[190:193], v[34:49]
	v_cvt_pk_bf16_f32 v194, v75, v76
	v_cvt_pk_bf16_f32 v195, v77, v78
	v_cvt_pk_bf16_f32 v196, v79, v80
	v_cvt_pk_bf16_f32 v197, v81, v82
	v_exp_f32_e32 v83, v83
	v_exp_f32_e32 v84, v84
	v_exp_f32_e32 v85, v85
	v_mfma_f32_32x32x16_bf16 v[50:65], v[206:209], v[194:197], v[50:65]
	v_exp_f32_e32 v86, v86
	v_exp_f32_e32 v87, v87
	v_exp_f32_e32 v88, v88
	v_exp_f32_e32 v89, v89
	v_exp_f32_e32 v90, v90
	v_sub_f32_e32 v91, v214, v181
	v_sub_f32_e32 v92, v215, v181
	v_mfma_f32_32x32x16_bf16 v[34:49], v[198:201], v[194:197], v[34:49]
	ds_read_b64_tr_b16 v[210:211], v245 offset:0x80
	ds_read_b64_tr_b16 v[212:213], v245 offset:0x980
	ds_read_b64_tr_b16 v[206:207], v245 offset:0x1280
	ds_read_b64_tr_b16 v[208:209], v245 offset:0x1b80
	ds_read_b64_tr_b16 v[202:203], v245 offset:0xc0
	ds_read_b64_tr_b16 v[204:205], v245 offset:0x9c0
	ds_read_b64_tr_b16 v[198:199], v245 offset:0x12c0
	ds_read_b64_tr_b16 v[200:201], v245 offset:0x1bc0
	s_waitcnt lgkmcnt(0)
	s_waitcnt lgkmcnt(0)
	v_sub_f32_e32 v93, v216, v181
	v_sub_f32_e32 v94, v217, v181
	v_sub_f32_e32 v95, v218, v181
	v_sub_f32_e32 v96, v219, v181
	v_sub_f32_e32 v97, v220, v181
	v_mfma_f32_32x32x16_bf16 v[18:33], v[210:213], v[190:193], v[18:33]
	v_sub_f32_e32 v181, v221, v181
	v_exp_f32_e32 v91, v91
	v_exp_f32_e32 v92, v92
	v_exp_f32_e32 v93, v93
	v_exp_f32_e32 v94, v94
	v_exp_f32_e32 v95, v95
	v_exp_f32_e32 v96, v96
	v_mfma_f32_32x32x16_bf16 v[2:17], v[202:205], v[190:193], v[2:17]
	v_cvt_pk_bf16_f32 v190, v83, v84
	v_cvt_pk_bf16_f32 v191, v85, v86
	v_cvt_pk_bf16_f32 v192, v87, v88
	v_cvt_pk_bf16_f32 v193, v89, v90
	v_exp_f32_e32 v97, v97
	v_exp_f32_e32 v181, v181
	s_andn2_b64 vcc, exec, s[14:15]
	v_mfma_f32_32x32x16_bf16 v[18:33], v[206:209], v[194:197], v[18:33]
	v_mfma_f32_32x32x16_bf16 v[2:17], v[198:201], v[194:197], v[2:17]
	ds_read_b64_tr_b16 v[210:211], v246 offset:0
	ds_read_b64_tr_b16 v[212:213], v246 offset:0x900
	ds_read_b64_tr_b16 v[206:207], v246 offset:0x1200
	ds_read_b64_tr_b16 v[208:209], v246 offset:0x1b00
	ds_read_b64_tr_b16 v[202:203], v246 offset:64
	ds_read_b64_tr_b16 v[204:205], v246 offset:0x940
	ds_read_b64_tr_b16 v[198:199], v246 offset:0x1240
	ds_read_b64_tr_b16 v[200:201], v246 offset:0x1b40
	s_waitcnt lgkmcnt(0)
	v_cvt_pk_bf16_f32 v194, v91, v92
	v_cvt_pk_bf16_f32 v195, v93, v94
	v_cvt_pk_bf16_f32 v196, v95, v96
	v_cvt_pk_bf16_f32 v197, v97, v181
	v_mfma_f32_32x32x16_bf16 v[50:65], v[210:213], v[190:193], v[50:65]
	v_mfma_f32_32x32x16_bf16 v[34:49], v[202:205], v[190:193], v[34:49]
	v_mfma_f32_32x32x16_bf16 v[50:65], v[206:209], v[194:197], v[50:65]
	v_mfma_f32_32x32x16_bf16 v[34:49], v[198:201], v[194:197], v[34:49]
	ds_read_b64_tr_b16 v[210:211], v246 offset:0x80
	ds_read_b64_tr_b16 v[212:213], v246 offset:0x980
	ds_read_b64_tr_b16 v[206:207], v246 offset:0x1280
	ds_read_b64_tr_b16 v[208:209], v246 offset:0x1b80
	ds_read_b64_tr_b16 v[202:203], v246 offset:0xc0
	ds_read_b64_tr_b16 v[204:205], v246 offset:0x9c0
	ds_read_b64_tr_b16 v[198:199], v246 offset:0x12c0
	ds_read_b64_tr_b16 v[200:201], v246 offset:0x1bc0
	s_waitcnt lgkmcnt(0)
	s_nop 0
	v_mfma_f32_32x32x16_bf16 v[18:33], v[210:213], v[190:193], v[18:33]
	v_mfma_f32_32x32x16_bf16 v[2:17], v[202:205], v[190:193], v[2:17]
	v_mfma_f32_32x32x16_bf16 v[18:33], v[206:209], v[194:197], v[18:33]
	v_mfma_f32_32x32x16_bf16 v[2:17], v[198:201], v[194:197], v[2:17]
	s_cbranch_vccnz .LBB0_265
	s_cmp_gt_i32 s21, -1
	s_cbranch_scc0 .Lrw_win2_orig
	s_waitcnt vmcnt(7)
	ds_write_b128 v241, v[146:149]
	s_waitcnt vmcnt(6)
	ds_write_b128 v241, v[150:153] offset:8704
	s_waitcnt vmcnt(5)
	ds_write_b128 v238, v[154:157] offset:17408
	s_waitcnt vmcnt(4)
	ds_write_b128 v238, v[158:161] offset:26624
	s_branch .Lrw_win2_done
; DI void coop_compute(AttnAcc& a, const bf16x8 (&qf)[8], char* stg, const int lo, const int hi, int lane) {
;     ...
;   for (int hf = 0; hf < 2; ++hf)
; #pragma unroll
;     for (int i = 0; i < 16; ++i) { const float pv = __builtin_amdgcn_exp2f(st[hf][i] - msafe); st[hf][i] = pv; ls += pv; }
;   a.l = a.l * alpha + ls;
.Lrw_win2_orig:
	s_waitcnt vmcnt(3)
	ds_write_b128 v241, v[146:149]
	s_waitcnt vmcnt(2)
	ds_write_b128 v241, v[150:153] offset:8704
	s_waitcnt vmcnt(1)
	ds_write_b128 v238, v[154:157] offset:17408
	s_waitcnt vmcnt(0)
	ds_write_b128 v238, v[158:161] offset:26624
.Lrw_win2_done:
.LBB0_265:
	v_add_f32_e32 v67, 0, v67
	v_add_f32_e32 v67, v68, v67
	v_add_f32_e32 v67, v69, v67
	v_add_f32_e32 v67, v70, v67
	v_add_f32_e32 v67, v71, v67
	v_add_f32_e32 v67, v72, v67
	v_add_f32_e32 v67, v73, v67
	v_add_f32_e32 v67, v74, v67
	v_add_f32_e32 v67, v75, v67
	v_add_f32_e32 v67, v76, v67
	v_add_f32_e32 v67, v77, v67
	v_add_f32_e32 v67, v78, v67
	v_add_f32_e32 v67, v79, v67
	v_add_f32_e32 v67, v80, v67
	v_add_f32_e32 v67, v81, v67
	v_add_f32_e32 v67, v82, v67
	v_add_f32_e32 v67, v83, v67
	v_add_f32_e32 v67, v84, v67
	v_add_f32_e32 v67, v85, v67
	v_add_f32_e32 v67, v86, v67
	v_add_f32_e32 v67, v87, v67
	v_add_f32_e32 v67, v88, v67
	v_add_f32_e32 v67, v89, v67
	v_add_f32_e32 v67, v90, v67
	v_add_f32_e32 v67, v91, v67
	v_add_f32_e32 v67, v92, v67
	v_add_f32_e32 v67, v93, v67
	v_add_f32_e32 v67, v94, v67
	v_add_f32_e32 v67, v95, v67
	v_add_f32_e32 v67, v96, v67
	v_add_f32_e32 v67, v97, v67
	v_add_f32_e32 v181, v181, v67
	s_add_u32 s0, s16, -1
	v_fmac_f32_e32 v181, v175, v66
	s_addc_u32 s1, s17, -1
	s_and_b64 s[16:17], s[0:1], s[16:17]
	v_mov_b32_e32 v175, v181
	s_mov_b64 s[0:1], s[12:13]
	s_waitcnt lgkmcnt(0)
	s_barrier
	s_and_b64 vcc, exec, s[0:1]
	s_mov_b32 s2, s7
	s_mov_b32 s20, s21
	s_cbranch_vccz .LBB0_244

.Lpj48_loop:
	v_or_b32_e32 v122, 0x10000, v200
	v_add_u32_e32 v134, 0x10400, v200
	v_add_u32_e32 v138, 0x10800, v200
	v_add_u32_e32 v142, 0x10c00, v200
	ds_read_b128 v[122:125], v122
	ds_read_b128 v[134:137], v134
	ds_read_b128 v[138:141], v138
	ds_read_b128 v[142:145], v142
	s_add_i32 s1, s0, -2
	s_cmp_lt_u32 s1, 30
	s_cselect_b32 s3, s4, s16
	s_cselect_b32 s5, s2, s15
	v_add_u32_e32 v181, 0xc000, v179
	v_add_u32_e32 v180, 0xfffc0000, v0
	v_readfirstlane_b32 s6, v181
	s_mov_b32 m0, s6
	ds_read_b128 v[146:149], v199
	ds_read_b128 v[150:153], v199 offset:1024
	ds_read_b128 v[154:157], v199 offset:2048
	ds_read_b128 v[158:161], v199 offset:3072
	ds_read_b128 v[162:165], v199 offset:4096
	ds_read_b128 v[166:169], v199 offset:5120
	ds_read_b128 v[170:173], v199 offset:6144
	ds_read_b128 v[174:177], v199 offset:7168
	global_load_lds_dwordx4 v180, s[80:81]
	v_add_u32_e32 v180, 0xe000, v179
	s_nop 0
	v_readfirstlane_b32 s6, v180
	s_mov_b32 m0, s6
	s_nop 0
	global_load_lds_dwordx4 v0, s[80:81]
	s_waitcnt lgkmcnt(8)
	s_barrier
	s_waitcnt lgkmcnt(0)
	s_setprio 1
	s_waitcnt lgkmcnt(0)
	v_mfma_f32_16x16x32_bf16 v[130:133], v[122:125], v[146:149], v[130:133]
	v_mfma_f32_16x16x32_bf16 v[110:113], v[122:125], v[154:157], v[110:113]
	v_mfma_f32_16x16x32_bf16 v[94:97], v[122:125], v[162:165], v[94:97]
	v_mfma_f32_16x16x32_bf16 v[78:81], v[122:125], v[170:173], v[78:81]
	v_mfma_f32_16x16x32_bf16 v[130:133], v[134:137], v[150:153], v[130:133]
	v_mfma_f32_16x16x32_bf16 v[110:113], v[134:137], v[158:161], v[110:113]
	v_mfma_f32_16x16x32_bf16 v[94:97], v[134:137], v[166:169], v[94:97]
	v_mfma_f32_16x16x32_bf16 v[78:81], v[134:137], v[174:177], v[78:81]
	s_setprio 0
	s_barrier
	s_cselect_b32 s6, s0, 0
	s_lshl_b32 s3, s3, 11
	s_lshl_b32 s7, s6, 6
	s_or_b32 s10, s3, s7
	s_lshl_b32 s10, s10, 1
	v_readfirstlane_b32 s11, v186
	v_or_b32_e32 v180, 0x14000, v200
	v_add_u32_e32 v202, 0x14400, v200
	v_add_u32_e32 v206, 0x14800, v200
	v_add_u32_e32 v210, 0x14c00, v200
	v_add_u32_e32 v214, s10, v184
	s_mov_b32 m0, s11
	ds_read_b128 v[180:183], v180
	ds_read_b128 v[202:205], v202
	ds_read_b128 v[206:209], v206
	ds_read_b128 v[210:213], v210
	global_load_lds_dwordx4 v214, s[74:75]
	v_add_u32_e32 v214, s10, v185
	v_readfirstlane_b32 s10, v187
	s_mov_b32 m0, s10
	s_nop 0
	global_load_lds_dwordx4 v214, s[74:75]
	s_barrier
	s_waitcnt lgkmcnt(0)
	s_setprio 1
	s_waitcnt lgkmcnt(0)
	s_setprio 0
	s_lshl_b32 s10, s5, 11
	s_or_b32 s11, s10, s7
	s_lshl_b32 s11, s11, 1
	v_readfirstlane_b32 s18, v179
	v_add_u32_e32 v214, s11, v184
	s_mov_b32 m0, s18
	s_barrier
	ds_read_b128 v[146:149], v199 offset:16384
	ds_read_b128 v[150:153], v199 offset:17408
	ds_read_b128 v[154:157], v199 offset:18432
	ds_read_b128 v[158:161], v199 offset:19456
	ds_read_b128 v[162:165], v199 offset:20480
	ds_read_b128 v[166:169], v199 offset:21504
	ds_read_b128 v[170:173], v199 offset:22528
	ds_read_b128 v[174:177], v199 offset:23552
	global_load_lds_dwordx4 v214, s[80:81]
	v_add_u32_e32 v214, s11, v185
	v_readfirstlane_b32 s11, v188
	s_mov_b32 m0, s11
	s_nop 0
	global_load_lds_dwordx4 v214, s[80:81]
	s_barrier
	s_waitcnt lgkmcnt(0)
	s_setprio 1
	s_waitcnt lgkmcnt(0)
	v_mfma_f32_16x16x32_bf16 v[62:65], v[122:125], v[146:149], v[62:65]
	v_mfma_f32_16x16x32_bf16 v[46:49], v[122:125], v[154:157], v[46:49]
	v_mfma_f32_16x16x32_bf16 v[30:33], v[122:125], v[162:165], v[30:33]
	v_mfma_f32_16x16x32_bf16 v[14:17], v[122:125], v[170:173], v[14:17]
	v_mfma_f32_16x16x32_bf16 v[62:65], v[134:137], v[150:153], v[62:65]
	v_mfma_f32_16x16x32_bf16 v[46:49], v[134:137], v[158:161], v[46:49]
	v_mfma_f32_16x16x32_bf16 v[30:33], v[134:137], v[166:169], v[30:33]
	v_mfma_f32_16x16x32_bf16 v[14:17], v[134:137], v[174:177], v[14:17]
	s_setprio 0
	s_barrier
	s_or_b32 s11, s3, 0x40000
	s_or_b32 s18, s11, s7
	s_lshl_b32 s18, s18, 1
	v_readfirstlane_b32 s19, v189
	v_add_u32_e32 v122, s18, v184
	s_mov_b32 m0, s19
	s_nop 0
	global_load_lds_dwordx4 v122, s[74:75]
	v_add_u32_e32 v122, s18, v185
	v_readfirstlane_b32 s18, v190
	s_mov_b32 m0, s18
	s_nop 0
	global_load_lds_dwordx4 v122, s[74:75]
	s_waitcnt vmcnt(6)
	s_barrier
	s_setprio 1
	s_setprio 0
	v_or_b32_e32 v122, 0x18000, v200
	v_add_u32_e32 v134, 0x18400, v200
	v_add_u32_e32 v138, 0x18800, v200
	v_add_u32_e32 v142, 0x18c00, v200
	s_barrier
	ds_read_b128 v[122:125], v122
	ds_read_b128 v[134:137], v134
	ds_read_b128 v[138:141], v138
	ds_read_b128 v[142:145], v142
	s_lshl_b32 s5, s5, 12
	s_lshl_b32 s6, s6, 7
	s_add_i32 s5, s6, s5
	s_add_i32 s5, s5, 0x80000
	v_readfirstlane_b32 s6, v191
	v_add_u32_e32 v180, s5, v184
	s_mov_b32 m0, s6
	ds_read_b128 v[146:149], v199 offset:32768
	ds_read_b128 v[150:153], v199 offset:33792
	ds_read_b128 v[154:157], v199 offset:34816
	ds_read_b128 v[158:161], v199 offset:35840
	ds_read_b128 v[162:165], v199 offset:36864
	ds_read_b128 v[166:169], v199 offset:37888
	ds_read_b128 v[170:173], v199 offset:38912
	ds_read_b128 v[174:177], v199 offset:39936
	global_load_lds_dwordx4 v180, s[80:81]
	v_add_u32_e32 v180, s5, v185
	v_readfirstlane_b32 s5, v192
	s_mov_b32 m0, s5
	s_nop 0
	global_load_lds_dwordx4 v180, s[80:81]
	s_waitcnt lgkmcnt(8)
	s_barrier
	s_waitcnt lgkmcnt(0)
	s_setprio 1
	s_waitcnt lgkmcnt(0)
	v_mfma_f32_16x16x32_bf16 v[130:133], v[122:125], v[146:149], v[130:133]
	v_mfma_f32_16x16x32_bf16 v[110:113], v[122:125], v[154:157], v[110:113]
	v_mfma_f32_16x16x32_bf16 v[94:97], v[122:125], v[162:165], v[94:97]
	v_mfma_f32_16x16x32_bf16 v[78:81], v[122:125], v[170:173], v[78:81]
	v_mfma_f32_16x16x32_bf16 v[130:133], v[134:137], v[150:153], v[130:133]
	v_mfma_f32_16x16x32_bf16 v[110:113], v[134:137], v[158:161], v[110:113]
	v_mfma_f32_16x16x32_bf16 v[94:97], v[134:137], v[166:169], v[94:97]
	v_mfma_f32_16x16x32_bf16 v[78:81], v[134:137], v[174:177], v[78:81]
	s_setprio 0
	s_barrier
	s_or_b32 s5, s7, 64
	s_or_b32 s3, s5, s3
	s_lshl_b32 s3, s3, 1
	v_readfirstlane_b32 s6, v193
	v_or_b32_e32 v180, 0x1c000, v200
	v_add_u32_e32 v202, 0x1c400, v200
	v_add_u32_e32 v206, 0x1c800, v200
	v_add_u32_e32 v210, 0x1cc00, v200
	v_add_u32_e32 v214, s3, v184
	s_mov_b32 m0, s6
	ds_read_b128 v[180:183], v180
	ds_read_b128 v[202:205], v202
	ds_read_b128 v[206:209], v206
	ds_read_b128 v[210:213], v210
	global_load_lds_dwordx4 v214, s[74:75]
	v_add_u32_e32 v214, s3, v185
	v_readfirstlane_b32 s3, v194
	s_mov_b32 m0, s3
	s_nop 0
	global_load_lds_dwordx4 v214, s[74:75]
	s_barrier
	s_waitcnt lgkmcnt(0)
	s_setprio 1
	s_waitcnt lgkmcnt(0)
	s_setprio 0
	s_or_b32 s3, s5, s10
	s_lshl_b32 s3, s3, 1
	v_readfirstlane_b32 s6, v195
	v_add_u32_e32 v214, s3, v184
	s_mov_b32 m0, s6
	s_barrier
	ds_read_b128 v[146:149], v199 offset:49152
	ds_read_b128 v[150:153], v199 offset:50176
	ds_read_b128 v[154:157], v199 offset:51200
	ds_read_b128 v[158:161], v199 offset:52224
	ds_read_b128 v[162:165], v199 offset:53248
	ds_read_b128 v[166:169], v199 offset:54272
	ds_read_b128 v[170:173], v199 offset:55296
	ds_read_b128 v[174:177], v199 offset:56320
	global_load_lds_dwordx4 v214, s[80:81]
	v_add_u32_e32 v214, s3, v185
	v_readfirstlane_b32 s3, v196
	s_mov_b32 m0, s3
	s_nop 0
	global_load_lds_dwordx4 v214, s[80:81]
	s_barrier
	s_waitcnt lgkmcnt(0)
	s_setprio 1
	s_waitcnt lgkmcnt(0)
	v_mfma_f32_16x16x32_bf16 v[62:65], v[122:125], v[146:149], v[62:65]
	v_mfma_f32_16x16x32_bf16 v[46:49], v[122:125], v[154:157], v[46:49]
	v_mfma_f32_16x16x32_bf16 v[30:33], v[122:125], v[162:165], v[30:33]
	v_mfma_f32_16x16x32_bf16 v[14:17], v[122:125], v[170:173], v[14:17]
	v_mfma_f32_16x16x32_bf16 v[62:65], v[134:137], v[150:153], v[62:65]
	v_mfma_f32_16x16x32_bf16 v[46:49], v[134:137], v[158:161], v[46:49]
	v_mfma_f32_16x16x32_bf16 v[30:33], v[134:137], v[166:169], v[30:33]
	v_mfma_f32_16x16x32_bf16 v[14:17], v[134:137], v[174:177], v[14:17]
	s_setprio 0
	s_barrier
	s_or_b32 s3, s11, s5
	s_lshl_b32 s3, s3, 1
	v_readfirstlane_b32 s5, v197
	v_add_u32_e32 v122, s3, v184
	s_mov_b32 m0, s5
	s_nop 0
	global_load_lds_dwordx4 v122, s[74:75]
	v_add_u32_e32 v122, s3, v185
	v_readfirstlane_b32 s3, v198
	s_mov_b32 m0, s3
	s_nop 0
	global_load_lds_dwordx4 v122, s[74:75]
	s_waitcnt vmcnt(6)
	s_barrier
	s_setprio 1
	s_setprio 0
	s_add_i32 s0, s0, 2
	s_cmp_gt_u32 s1, 29
	v_add_u32_e32 v0, 0x100, v0
	s_barrier
	s_cbranch_scc0 .Lpj48_loop
	s_branch .Lpj48_done

; template <class EPI>
; DI void gemm_stream(const u16* __restrict__ A, const u16* __restrict__ Bt, const int K, const int nM, const int nN,
;                     const int bid, const int nb, const int tid, EPI epi) {
;     ...
;   GemmAcc acc = {};
;     ...
;   for (int id = bid; id < ntot; id += nb) {
;     const int idn = id + nb;
;     int pm2 = pm, pn2 = pn;
;     if (idn < ntot) gemm_tile_coords(idn, nM, nN, pm2, pn2);
;     const int brow2 = pm2 * BM, bcol2 = pn2 * BM;
;     for (int t = 0; t < nt; t += 2) {
;       const bool inside = (t + 2 < nt);
;       const int brs = inside ? brow : brow2, bcs = inside ? bcol : bcol2, t2 = inside ? t + 2 : 0;
;       bf16x8 At[4][2], B0[2][2], B1[2][2];
;       PAIR(brow, bcol, t + 1, brs, bcs, t2, t2 + 1)
.LBB0_413:
	s_cmp_eq_u32 s17, 48
	s_cselect_b64 vcc, -1, 0
	v_mov_b32_e32 v2, 0
	s_lshl_b32 s15, s12, 8
	s_lshl_b32 s16, s14, 8
	v_lshl_add_u32 v0, s2, 12, v201
	s_mov_b32 s0, 2
	v_mov_b32_e32 v3, v2
	v_mov_b32_e32 v4, v2
	v_mov_b32_e32 v5, v2
	v_mov_b32_e32 v6, v2
	v_mov_b32_e32 v7, v2
	v_mov_b32_e32 v8, v2
	v_mov_b32_e32 v9, v2
	v_mov_b32_e32 v18, v2
	v_mov_b32_e32 v19, v2
	v_mov_b32_e32 v20, v2
	v_mov_b32_e32 v21, v2
	v_mov_b32_e32 v22, v2
	v_mov_b32_e32 v23, v2
	v_mov_b32_e32 v24, v2
	v_mov_b32_e32 v25, v2
	v_mov_b32_e32 v34, v2
	v_mov_b32_e32 v35, v2
	v_mov_b32_e32 v36, v2
	v_mov_b32_e32 v37, v2
	v_mov_b32_e32 v38, v2
	v_mov_b32_e32 v39, v2
	v_mov_b32_e32 v40, v2
	v_mov_b32_e32 v41, v2
	v_mov_b32_e32 v50, v2
	v_mov_b32_e32 v51, v2
	v_mov_b32_e32 v52, v2
	v_mov_b32_e32 v53, v2
	v_mov_b32_e32 v54, v2
	v_mov_b32_e32 v55, v2
	v_mov_b32_e32 v56, v2
	v_mov_b32_e32 v57, v2
	v_mov_b32_e32 v10, v2
	v_mov_b32_e32 v11, v2
	v_mov_b32_e32 v12, v2
	v_mov_b32_e32 v13, v2
	v_mov_b32_e32 v14, v2
	v_mov_b32_e32 v15, v2
	v_mov_b32_e32 v16, v2
	v_mov_b32_e32 v17, v2
	v_mov_b32_e32 v26, v2
	v_mov_b32_e32 v27, v2
	v_mov_b32_e32 v28, v2
	v_mov_b32_e32 v29, v2
	v_mov_b32_e32 v30, v2
	v_mov_b32_e32 v31, v2
	v_mov_b32_e32 v32, v2
	v_mov_b32_e32 v33, v2
	v_mov_b32_e32 v42, v2
	v_mov_b32_e32 v43, v2
	v_mov_b32_e32 v44, v2
	v_mov_b32_e32 v45, v2
	v_mov_b32_e32 v46, v2
	v_mov_b32_e32 v47, v2
	v_mov_b32_e32 v48, v2
	v_mov_b32_e32 v49, v2
	v_mov_b32_e32 v58, v2
	v_mov_b32_e32 v59, v2
	v_mov_b32_e32 v60, v2
	v_mov_b32_e32 v61, v2
	v_mov_b32_e32 v62, v2
	v_mov_b32_e32 v63, v2
	v_mov_b32_e32 v64, v2
	v_mov_b32_e32 v65, v2
	v_mov_b32_e32 v66, v2
	v_mov_b32_e32 v67, v2
	v_mov_b32_e32 v68, v2
	v_mov_b32_e32 v69, v2
	v_mov_b32_e32 v70, v2
	v_mov_b32_e32 v71, v2
	v_mov_b32_e32 v72, v2
	v_mov_b32_e32 v73, v2
	v_mov_b32_e32 v82, v2
	v_mov_b32_e32 v83, v2
	v_mov_b32_e32 v84, v2
	v_mov_b32_e32 v85, v2
	v_mov_b32_e32 v86, v2
	v_mov_b32_e32 v87, v2
	v_mov_b32_e32 v88, v2
	v_mov_b32_e32 v89, v2
	v_mov_b32_e32 v98, v2
	v_mov_b32_e32 v99, v2
	v_mov_b32_e32 v100, v2
	v_mov_b32_e32 v101, v2
	v_mov_b32_e32 v102, v2
	v_mov_b32_e32 v103, v2
	v_mov_b32_e32 v104, v2
	v_mov_b32_e32 v105, v2
	v_mov_b32_e32 v114, v2
	v_mov_b32_e32 v115, v2
	v_mov_b32_e32 v116, v2
	v_mov_b32_e32 v117, v2
	v_mov_b32_e32 v118, v2
	v_mov_b32_e32 v119, v2
	v_mov_b32_e32 v120, v2
	v_mov_b32_e32 v121, v2
	v_mov_b32_e32 v74, v2
	v_mov_b32_e32 v75, v2
	v_mov_b32_e32 v76, v2
	v_mov_b32_e32 v77, v2
	v_mov_b32_e32 v78, v2
	v_mov_b32_e32 v79, v2
	v_mov_b32_e32 v80, v2
	v_mov_b32_e32 v81, v2
	v_mov_b32_e32 v90, v2
	v_mov_b32_e32 v91, v2
	v_mov_b32_e32 v92, v2
	v_mov_b32_e32 v93, v2
	v_mov_b32_e32 v94, v2
	v_mov_b32_e32 v95, v2
	v_mov_b32_e32 v96, v2
	v_mov_b32_e32 v97, v2
	v_mov_b32_e32 v106, v2
	v_mov_b32_e32 v107, v2
	v_mov_b32_e32 v108, v2
	v_mov_b32_e32 v109, v2
	v_mov_b32_e32 v110, v2
	v_mov_b32_e32 v111, v2
	v_mov_b32_e32 v112, v2
	v_mov_b32_e32 v113, v2
	v_mov_b32_e32 v126, v2
	v_mov_b32_e32 v127, v2
	v_mov_b32_e32 v128, v2
	v_mov_b32_e32 v129, v2
	v_mov_b32_e32 v130, v2
	v_mov_b32_e32 v131, v2
	v_mov_b32_e32 v132, v2
	v_mov_b32_e32 v133, v2
	s_cbranch_vccnz .Lpj48_loop

; DI void gemm_proj(const Params& p, int bid, int nb, int tid) {
;     ...
;   gemm_stream(A, Bt, 2048, nM, nN, bid, nb, tid, [&](GemmAcc& acc, const int brow, const int bcol, const int pn) {
;     GEMM_IDS
;     const bool rope_tile = (pn < 12) || (pn >= 18 && pn < 26) || pn == 28 || pn == 30;
;     const bool kv_tile = (pn >= 28 && pn < 32);
.Lpj48_done:
	v_mov_b32_e32 v0, v239
	s_cmp_lt_i32 s17, 12
	s_mov_b64 s[0:1], -1
	s_cbranch_scc1 .LBB0_418
	s_cmp_gt_u32 s17, 30
	s_mov_b64 s[0:1], 0
	s_cbranch_scc1 .LBB0_418
	s_lshr_b32 s0, 0x53fc0000, s17
	s_bitcmp1_b32 s0, 0
	s_cselect_b64 s[0:1], -1, 0
